# 672 W_DN0 conversion tiles moved from phase 0 into the idle tail of the in_proj GEMM phase
# speedup vs baseline: 1.0396x; 1.0040x over previous
.LBB0_943:
	s_andn2_b64 vcc, exec, s[6:7]
	s_cbranch_vccnz .LBB0_945
	s_add_i32 s17, s0, 0xca0
	s_movk_i32 s10, 0xe0
	s_movk_i32 s11, 0x14a0

.LBB0_946:
	s_and_b64 s[4:5], s[4:5], exec
	s_movk_i32 s1, 0xcc0
	s_cselect_b32 s11, s1, 0x1aa0
	s_mov_b32 s17, s0
	s_mov_b32 s10, s50
